# rebalanced static attention SCHED table (same 581 items, re-packed using measured per-item costs)
# speedup vs baseline: 1.0099x; 1.0034x over previous
_ZL5SCHED:
	.short	360
	.short	65535
	.short	65535
	.short	424
	.short	65535
	.short	65535
	.short	422
	.short	65535
	.short	65535
	.short	487
	.short	65535
	.short	65535
	.short	486
	.short	65535
	.short	65535
	.short	488
	.short	65535
	.short	65535
	.short	359
	.short	65535
	.short	65535
	.short	423
	.short	65535
	.short	65535
	.short	420
	.short	385
	.short	65535
	.short	357
	.short	320
	.short	65535
	.short	485
	.short	256
	.short	65535
	.short	358
	.short	384
	.short	65535
	.short	421
	.short	128
	.short	65535
	.short	484
	.short	449
	.short	65535
	.short	356
	.short	193
	.short	65535
	.short	482
	.short	8
	.short	65535
	.short	353
	.short	4
	.short	65535
	.short	418
	.short	25
	.short	65535
	.short	354
	.short	63
	.short	65535
	.short	419
	.short	194
	.short	65535
	.short	355
	.short	322
	.short	65535
	.short	483
	.short	130
	.short	65535
	.short	481
	.short	67
	.short	65535
	.short	417
	.short	323
	.short	65535
	.short	95
	.short	1535
	.short	65535
	.short	1022
	.short	197
	.short	65535
	.short	350
	.short	117
	.short	65535
	.short	453
	.short	1470
	.short	65535
	.short	954
	.short	165
	.short	65535
	.short	479
	.short	99
	.short	65535
	.short	475
	.short	458
	.short	65535
	.short	480
	.short	69
	.short	65535
	.short	306
	.short	455
	.short	65535
	.short	325
	.short	1533
	.short	65535
	.short	297
	.short	263
	.short	65535
	.short	478
	.short	134
	.short	65535
	.short	305
	.short	327
	.short	65535
	.short	892
	.short	457
	.short	65535
	.short	292
	.short	177
	.short	65535
	.short	348
	.short	170
	.short	65535
	.short	295
	.short	166
	.short	65535
	.short	311
	.short	184
	.short	65535
	.short	1012
	.short	123
	.short	37
	.short	347
	.short	328
	.short	65535
	.short	352
	.short	324
	.short	65535
	.short	1023
	.short	113
	.short	65535
	.short	308
	.short	167
	.short	65535
	.short	169
	.short	1530
	.short	65535
	.short	296
	.short	145
	.short	65535
	.short	412
	.short	392
	.short	65535
	.short	887
	.short	393
	.short	65535
	.short	416
	.short	75
	.short	65535
	.short	287
	.short	154
	.short	65535
	.short	200
	.short	1402
	.short	65535
	.short	313
	.short	135
	.short	65535
	.short	298
	.short	142
	.short	65535
	.short	133
	.short	1407
	.short	65535
	.short	178
	.short	1466
	.short	65535
	.short	889
	.short	191
	.short	65535
	.short	415
	.short	102
	.short	65535
	.short	301
	.short	148
	.short	65535
	.short	1021
	.short	262
	.short	65535
	.short	286
	.short	188
	.short	65535
	.short	150
	.short	1531
	.short	65535
	.short	146
	.short	1404
	.short	65535
	.short	414
	.short	198
	.short	65535
	.short	201
	.short	1401
	.short	65535
	.short	309
	.short	137
	.short	65535
	.short	315
	.short	175
	.short	65535
	.short	476
	.short	456
	.short	65535
	.short	293
	.short	164
	.short	65535
	.short	955
	.short	179
	.short	65535
	.short	289
	.short	158
	.short	65535
	.short	303
	.short	157
	.short	65535
	.short	318
	.short	174
	.short	65535
	.short	454
	.short	1469
	.short	65535
	.short	285
	.short	139
	.short	65535
	.short	959
	.short	98
	.short	65535
	.short	1018
	.short	163
	.short	65535
	.short	299
	.short	159
	.short	65535
	.short	182
	.short	1532
	.short	65535
	.short	294
	.short	144
	.short	65535
	.short	389
	.short	1534
	.short	65535
	.short	958
	.short	261
	.short	65535
	.short	948
	.short	92
	.short	45
	.short	260
	.short	192
	.short	1406
	.short	949
	.short	126
	.short	41
	.short	953
	.short	48
	.short	44
	.short	5
	.short	54
	.short	1465
	.short	284
	.short	60
	.short	56
	.short	1017
	.short	50
	.short	15
	.short	71
	.short	112
	.short	1395
	.short	109
	.short	29
	.short	1399
	.short	282
	.short	115
	.short	42
	.short	888
	.short	9
	.short	16
	.short	1020
	.short	186
	.short	65535
	.short	291
	.short	183
	.short	65535
	.short	288
	.short	172
	.short	65535
	.short	351
	.short	84
	.short	65535
	.short	312
	.short	161
	.short	65535
	.short	319
	.short	162
	.short	65535
	.short	314
	.short	152
	.short	65535
	.short	310
	.short	189
	.short	65535
	.short	317
	.short	391
	.short	65535
	.short	1019
	.short	151
	.short	65535
	.short	307
	.short	149
	.short	65535
	.short	413
	.short	160
	.short	65535
	.short	956
	.short	147
	.short	65535
	.short	300
	.short	176
	.short	65535
	.short	891
	.short	264
	.short	65535
	.short	957
	.short	390
	.short	65535
	.short	304
	.short	190
	.short	65535
	.short	125
	.short	1471
	.short	65535
	.short	290
	.short	181
	.short	65535
	.short	349
	.short	326
	.short	65535
	.short	171
	.short	1468
	.short	65535
	.short	477
	.short	153
	.short	65535
	.short	316
	.short	187
	.short	65535
	.short	302
	.short	199
	.short	65535
	.short	143
	.short	1405
	.short	65535
	.short	893
	.short	266
	.short	65535
	.short	411
	.short	394
	.short	65535
	.short	168
	.short	1467
	.short	65535
	.short	329
	.short	1463
	.short	65535
	.short	950
	.short	89
	.short	27
	.short	32
	.short	28
	.short	1529
	.short	890
	.short	20
	.short	58
	.short	409
	.short	141
	.short	321
	.short	76
	.short	55
	.short	1460
	.short	78
	.short	3
	.short	1526
	.short	345
	.short	127
	.short	57
	.short	474
	.short	119
	.short	14
	.short	952
	.short	118
	.short	257
	.short	90
	.short	7
	.short	1397
	.short	886
	.short	122
	.short	66
	.short	131
	.short	49
	.short	1528
	.short	100
	.short	51
	.short	1524
	.short	945
	.short	72
	.short	124
	.short	410
	.short	96
	.short	47
	.short	346
	.short	85
	.short	30
	.short	882
	.short	185
	.short	1
	.short	880
	.short	73
	.short	114
	.short	132
	.short	24
	.short	1527
	.short	884
	.short	106
	.short	26
	.short	110
	.short	70
	.short	1457
	.short	885
	.short	108
	.short	13
	.short	74
	.short	36
	.short	1525
	.short	281
	.short	80
	.short	387
	.short	111
	.short	195
	.short	1459
	.short	1016
	.short	97
	.short	65
	.short	156
	.short	59
	.short	1520
	.short	1009
	.short	81
	.short	86
	.short	451
	.short	35
	.short	1464
	.short	951
	.short	82
	.short	258
	.short	472
	.short	136
	.short	61
	.short	91
	.short	17
	.short	1462
	.short	895
	.short	94
	.short	11
	.short	881
	.short	155
	.short	450
	.short	77
	.short	259
	.short	1523
	.short	883
	.short	107
	.short	53
	.short	103
	.short	19
	.short	1461
	.short	116
	.short	52
	.short	1398
	.short	473
	.short	83
	.short	388
	.short	280
	.short	101
	.short	87
	.short	6
	.short	10
	.short	1403
	.short	894
	.short	104
	.short	23
	.short	79
	.short	34
	.short	1400
	.short	408
	.short	138
	.short	12
	.short	1014
	.short	88
	.short	18
	.short	1015
	.short	93
	.short	2
	.short	120
	.short	105
	.short	1521
	.short	1013
	.short	121
	.short	22
	.short	140
	.short	39
	.short	1394
	.short	343
	.short	173
	.short	46
	.short	938
	.short	202
	.short	21
	.short	873
	.short	330
	.short	62
	.short	1001
	.short	203
	.short	33
	.short	946
	.short	180
	.short	386
	.short	283
	.short	265
	.short	65535
	.short	268
	.short	1522
	.short	65535
	.short	1011
	.short	267
	.short	65535
	.short	204
	.short	1458
	.short	65535
	.short	470
	.short	220
	.short	65535
	.short	404
	.short	273
	.short	65535
	.short	879
	.short	269
	.short	65535
	.short	1008
	.short	461
	.short	65535
	.short	1006
	.short	217
	.short	65535
	.short	944
	.short	205
	.short	65535
	.short	344
	.short	460
	.short	65535
	.short	250
	.short	1390
	.short	65535
	.short	342
	.short	230
	.short	65535
	.short	1010
	.short	332
	.short	65535
	.short	947
	.short	331
	.short	65535
	.short	397
	.short	1456
	.short	65535
	.short	227
	.short	1454
	.short	65535
	.short	243
	.short	1453
	.short	65535
	.short	340
	.short	226
	.short	65535
	.short	207
	.short	1388
	.short	65535
	.short	874
	.short	245
	.short	65535
	.short	942
	.short	240
	.short	65535
	.short	398
	.short	1455
	.short	65535
	.short	270
	.short	1519
	.short	65535
	.short	209
	.short	1452
	.short	65535
	.short	237
	.short	1451
	.short	65535
	.short	407
	.short	222
	.short	65535
	.short	1003
	.short	234
	.short	65535
	.short	279
	.short	462
	.short	65535
	.short	1002
	.short	335
	.short	65535
	.short	1004
	.short	214
	.short	65535
	.short	271
	.short	1387
	.short	65535
	.short	255
	.short	1515
	.short	65535
	.short	937
	.short	401
	.short	65535
	.short	403
	.short	466
	.short	65535
	.short	399
	.short	1514
	.short	65535
	.short	216
	.short	1391
	.short	65535
	.short	341
	.short	239
	.short	65535
	.short	406
	.short	238
	.short	65535
	.short	253
	.short	1389
	.short	65535
	.short	247
	.short	1518
	.short	65535
	.short	1007
	.short	334
	.short	65535
	.short	252
	.short	1392
	.short	65535
	.short	877
	.short	246
	.short	65535
	.short	405
	.short	249
	.short	65535
	.short	471
	.short	213
	.short	65535
	.short	468
	.short	465
	.short	65535
	.short	396
	.short	1396
	.short	65535
	.short	339
	.short	337
	.short	65535
	.short	1005
	.short	254
	.short	65535
	.short	333
	.short	1393
	.short	65535
	.short	232
	.short	1517
	.short	65535
	.short	939
	.short	221
	.short	65535
	.short	876
	.short	212
	.short	65535
	.short	277
	.short	235
	.short	65535
	.short	463
	.short	1450
	.short	65535
	.short	941
	.short	211
	.short	65535
	.short	469
	.short	224
	.short	65535
	.short	940
	.short	231
	.short	65535
	.short	276
	.short	272
	.short	65535
	.short	242
	.short	1516
	.short	65535
	.short	878
	.short	251
	.short	65535
	.short	875
	.short	233
	.short	65535
	.short	336
	.short	1386
	.short	65535
	.short	943
	.short	206
	.short	65535
	.short	338
	.short	274
	.short	65535
	.short	278
	.short	225
	.short	65535
	.short	241
	.short	448
	.short	1385
	.short	459
	.short	38
	.short	1513
	.short	395
	.short	43
	.short	1449
	.short	467
	.short	218
	.short	0
	.short	219
	.short	228
	.short	68
	.short	275
	.short	208
	.short	64
	.short	402
	.short	223
	.short	129
	.short	236
	.short	244
	.short	452
	.short	464
	.short	248
	.short	31
	.short	215
	.short	229
	.short	196
	.short	400
	.short	210
	.short	40
	.size	_ZL5SCHED, 1536

	.type	__hip_cuid_3f0aab64d1338eba,@object
